# in-proj k/v epilogue head: row-sum, bias and gain loads issued together (one round trip instead of three)
# speedup vs baseline: 1.0005x; 1.0005x over previous
.LBB0_607:
	s_add_u32 s42, s94, s42
	s_addc_u32 s43, s95, s43
	s_ashr_i32 s4, s4, 6
	s_and_b32 s4, s4, -4
	s_add_i32 s4, s4, s18
	v_lshlrev_b64 v[130:131], 8, v[130:131]
	s_ashr_i32 s5, s4, 31
	v_lshl_add_u64 v[130:131], s[42:43], 0, v[130:131]
	v_lshlrev_b32_e32 v132, 1, v217
	v_mov_b32_e32 v133, v1
	s_lshl_b64 s[4:5], s[4:5], 17
	v_lshl_add_u64 v[192:193], v[130:131], 0, v[132:133]
	s_add_u32 s4, s88, s4
	v_lshlrev_b32_e32 v130, 9, v190
	s_addc_u32 s5, s89, s5
	v_and_b32_e32 v130, 0x19e00, v130
	v_mov_b32_e32 v131, v1
	v_lshl_add_u64 v[130:131], s[4:5], 0, v[130:131]
	v_lshl_add_u64 v[130:131], v[130:131], 0, s[54:55]
	v_lshl_add_u64 v[194:195], v[130:131], 0, v[0:1]
	v_cndmask_b32_e64 v130, 0, 1, s[60:61]
	s_mov_b64 s[56:57], -1
	s_and_b64 vcc, exec, s[48:49]
	v_cmp_ne_u32_e64 s[42:43], 1, v130
	s_cbranch_vccz .LBB0_625
	global_load_dwordx4 v[130:133], v[188:189], off
	global_load_dwordx4 v[134:137], v[188:189], off offset:256
	global_load_dwordx4 v[138:141], v[188:189], off offset:512
	global_load_dwordx4 v[142:145], v[188:189], off offset:768
	global_load_dwordx4 v[228:231], v[188:189], off offset:2048
	global_load_dwordx4 v[232:235], v[188:189], off offset:2304
	global_load_dwordx4 v[240:243], v[188:189], off offset:2560
	global_load_dwordx4 v[158:161], v[188:189], off offset:2816
	global_load_dwordx4 v[244:247], v[186:187], off
	global_load_dwordx4 v[248:251], v[186:187], off offset:64
	global_load_dwordx4 v[150:153], v[186:187], off offset:512
	global_load_dwordx4 v[218:221], v[186:187], off offset:576
	v_mov_b64_e32 v[196:197], v[194:195]
	v_mov_b64_e32 v[176:177], v[192:193]
	s_and_b64 vcc, exec, s[42:43]
	s_waitcnt vmcnt(8)
	v_mov_b32_e32 v146, v131
	v_mov_b32_e32 v147, v132
	v_mov_b32_e32 v131, v133
	v_mov_b32_e32 v132, v135
	v_mov_b32_e32 v133, v136
	v_mov_b32_e32 v135, v137
	v_mov_b32_e32 v136, v139
	v_mov_b32_e32 v137, v140
	v_mov_b32_e32 v139, v141
	v_mov_b32_e32 v140, v143
	v_mov_b32_e32 v141, v144
	v_mov_b32_e32 v143, v145
	v_pk_add_f32 v[130:131], v[146:147], v[130:131]
	v_pk_add_f32 v[132:133], v[132:133], v[134:135]
	v_pk_add_f32 v[134:135], v[136:137], v[138:139]
	v_pk_add_f32 v[136:137], v[140:141], v[142:143]
	v_add_f32_e32 v130, v130, v131
	v_add_f32_e32 v131, v132, v133
	v_add_f32_e32 v132, v134, v135
	v_add_f32_e32 v133, v136, v137
	v_fmamk_f32 v130, v130, 0x3a800000, v223
	v_fmamk_f32 v131, v131, 0x3a800000, v223
	v_fmamk_f32 v132, v132, 0x3a800000, v223
	v_fmamk_f32 v133, v133, 0x3a800000, v223
	v_rsq_f32_e32 v148, v130
	v_rsq_f32_e32 v174, v131
	v_rsq_f32_e32 v172, v132
	v_rsq_f32_e32 v170, v133
	s_waitcnt vmcnt(7)
	v_add_f32_e32 v228, v228, v229
	v_add_f32_e32 v229, v230, v231
	s_waitcnt vmcnt(6)
	v_add_f32_e32 v230, v232, v233
	v_add_f32_e32 v231, v234, v235
	s_waitcnt vmcnt(5)
	v_add_f32_e32 v232, v240, v241
	v_add_f32_e32 v233, v242, v243
	s_waitcnt vmcnt(4)
	v_add_f32_e32 v234, v158, v159
	v_add_f32_e32 v235, v160, v161
	v_add_f32_e32 v228, v228, v229
	v_add_f32_e32 v229, v230, v231
	v_add_f32_e32 v230, v232, v233
	v_add_f32_e32 v231, v234, v235
	v_fmamk_f32 v228, v228, 0x3a800000, v223
	v_fmamk_f32 v229, v229, 0x3a800000, v223
	v_fmamk_f32 v230, v230, 0x3a800000, v223
	v_fmamk_f32 v231, v231, 0x3a800000, v223
	v_rsq_f32_e32 v168, v228
	v_rsq_f32_e32 v166, v229
	v_rsq_f32_e32 v164, v230
	v_rsq_f32_e32 v162, v231
	s_waitcnt vmcnt(3)
	v_mov_b64_e32 v[142:143], v[244:245]
	v_mov_b64_e32 v[144:145], v[246:247]
	v_pk_fma_f32 v[158:159], v[126:127], v[148:149], v[142:143] op_sel_hi:[1,0,1]
	v_pk_fma_f32 v[160:161], v[128:129], v[148:149], v[144:145] op_sel_hi:[1,0,1]
	s_waitcnt vmcnt(2)
	v_mov_b64_e32 v[138:139], v[248:249]
	v_mov_b64_e32 v[140:141], v[250:251]
	v_pk_fma_f32 v[154:155], v[122:123], v[148:149], v[138:139] op_sel_hi:[1,0,1]
	v_pk_fma_f32 v[156:157], v[124:125], v[148:149], v[140:141] op_sel_hi:[1,0,1]
	s_waitcnt vmcnt(1)
	v_mov_b64_e32 v[134:135], v[150:151]
	v_mov_b64_e32 v[136:137], v[152:153]
	v_pk_fma_f32 v[150:151], v[118:119], v[148:149], v[134:135] op_sel_hi:[1,0,1]
	v_pk_fma_f32 v[152:153], v[120:121], v[148:149], v[136:137] op_sel_hi:[1,0,1]
	s_waitcnt vmcnt(0)
	v_mov_b64_e32 v[130:131], v[218:219]
	v_mov_b64_e32 v[132:133], v[220:221]
	v_pk_fma_f32 v[146:147], v[114:115], v[148:149], v[130:131] op_sel_hi:[1,0,1]
	v_pk_fma_f32 v[148:149], v[116:117], v[148:149], v[132:133] op_sel_hi:[1,0,1]
	s_cbranch_vccnz .LBB0_610
	global_store_dwordx4 v[196:197], v[158:161], off
	global_store_dwordx4 v[196:197], v[154:157], off offset:64
	global_store_dwordx4 v[196:197], v[150:153], off offset:128
	global_store_dwordx4 v[196:197], v[146:149], off offset:192

.LBB0_625:
	s_and_b64 vcc, exec, s[56:57]
	s_cbranch_vccz .LBB0_659
	global_load_dwordx4 v[130:133], v[188:189], off
	global_load_dwordx4 v[134:137], v[188:189], off offset:256
	global_load_dwordx4 v[138:141], v[188:189], off offset:512
	global_load_dwordx4 v[142:145], v[188:189], off offset:768
	global_load_dwordx4 v[168:171], v[188:189], off offset:2048
	global_load_dwordx4 v[172:175], v[188:189], off offset:2304
	global_load_dwordx4 v[228:231], v[188:189], off offset:2560
	global_load_dwordx4 v[232:235], v[188:189], off offset:2816
	global_load_dwordx4 v[158:161], v[186:187], off
	global_load_dwordx4 v[154:157], v[186:187], off offset:64
	global_load_dwordx4 v[150:153], v[186:187], off offset:512
	global_load_dwordx4 v[146:149], v[186:187], off offset:576
	global_load_dwordx4 v[242:245], v0, s[26:27]
	global_load_dwordx4 v[246:249], v0, s[26:27] offset:64
	global_load_dwordx4 v[250:253], v0, s[26:27] offset:128
	v_or_b32_e32 v164, 1, v217
	v_or_b32_e32 v165, 2, v217
	v_or_b32_e32 v166, 3, v217
	v_cvt_f32_ubyte0_e32 v163, v217
	v_cvt_f32_ubyte0_e32 v164, v164
	v_cvt_f32_ubyte0_e32 v165, v165
	v_cvt_f32_ubyte0_e32 v166, v166
	v_mul_f32_e32 v163, 0xbf549a78, v163
	v_mul_f32_e32 v164, 0xbf549a78, v164
	v_mul_f32_e32 v165, 0xbf549a78, v165
	v_mul_f32_e32 v166, 0xbf549a78, v166
	v_exp_f32_e32 v163, v163
	v_exp_f32_e32 v164, v164
	v_exp_f32_e32 v165, v165
	v_exp_f32_e32 v166, v166
	v_mul_f32_e32 v220, 0.15915494, v163
	v_mul_f32_e32 v219, 0.15915494, v164
	v_mul_f32_e32 v218, 0.15915494, v165
	v_mul_f32_e32 v197, 0.15915494, v166
	v_mov_b32_e32 v226, v225
	v_and_b32_e32 v203, 63, v216
	v_cvt_f32_ubyte0_e32 v199, v203
	v_mov_b64_e32 v[210:211], v[192:193]
	v_mov_b64_e32 v[212:213], v[194:195]
	s_and_b64 vcc, exec, s[44:45]
	v_mul_f32_e32 v201, v220, v199
	v_mul_f32_e32 v239, v219, v199
	v_mul_f32_e32 v240, v197, v199
	s_waitcnt vmcnt(11)
	v_mov_b32_e32 v236, v131
	v_mov_b32_e32 v237, v132
	v_mov_b32_e32 v131, v133
	v_mov_b32_e32 v132, v135
	v_mov_b32_e32 v133, v136
	v_mov_b32_e32 v135, v137
	v_mov_b32_e32 v136, v139
	v_mov_b32_e32 v137, v140
	v_mov_b32_e32 v139, v141
	v_mov_b32_e32 v140, v143
	v_mov_b32_e32 v141, v144
	v_mov_b32_e32 v143, v145
	v_pk_add_f32 v[130:131], v[236:237], v[130:131]
	v_pk_add_f32 v[132:133], v[132:133], v[134:135]
	v_pk_add_f32 v[134:135], v[136:137], v[138:139]
	v_pk_add_f32 v[136:137], v[140:141], v[142:143]
	v_add_f32_e32 v130, v130, v131
	v_add_f32_e32 v131, v132, v133
	v_add_f32_e32 v132, v134, v135
	v_add_f32_e32 v133, v136, v137
	v_fmamk_f32 v130, v130, 0x3a800000, v223
	v_fmamk_f32 v131, v131, 0x3a800000, v223
	v_fmamk_f32 v132, v132, 0x3a800000, v223
	v_fmamk_f32 v133, v133, 0x3a800000, v223
	v_rsq_f32_e32 v162, v130
	v_rsq_f32_e32 v208, v131
	v_rsq_f32_e32 v206, v132
	v_rsq_f32_e32 v204, v133
	global_load_dwordx4 v[142:145], v0, s[26:27] offset:192
	s_waitcnt vmcnt(11)
	v_add_f32_e32 v168, v168, v169
	v_add_f32_e32 v169, v170, v171
	s_waitcnt vmcnt(10)
	v_add_f32_e32 v170, v172, v173
	v_add_f32_e32 v171, v174, v175
	s_waitcnt vmcnt(9)
	v_add_f32_e32 v172, v228, v229
	v_add_f32_e32 v173, v230, v231
	s_waitcnt vmcnt(8)
	v_add_f32_e32 v174, v232, v233
	v_add_f32_e32 v175, v234, v235
	v_add_f32_e32 v168, v168, v169
	v_add_f32_e32 v169, v170, v171
	v_add_f32_e32 v170, v172, v173
	v_add_f32_e32 v171, v174, v175
	v_fmamk_f32 v168, v168, 0x3a800000, v223
	v_fmamk_f32 v169, v169, 0x3a800000, v223
	v_fmamk_f32 v170, v170, 0x3a800000, v223
	v_fmamk_f32 v171, v171, 0x3a800000, v223
	v_rsq_f32_e32 v202, v168
	v_rsq_f32_e32 v200, v169
	v_rsq_f32_e32 v198, v170
	v_rsq_f32_e32 v196, v171
	s_waitcnt vmcnt(7)
	v_pk_fma_f32 v[164:165], v[128:129], v[162:163], v[160:161] op_sel_hi:[1,0,1]
	v_pk_fma_f32 v[166:167], v[126:127], v[162:163], v[158:159] op_sel_hi:[1,0,1]
	s_waitcnt vmcnt(6)
	v_pk_fma_f32 v[168:169], v[124:125], v[162:163], v[156:157] op_sel_hi:[1,0,1]
	v_pk_fma_f32 v[170:171], v[122:123], v[162:163], v[154:155] op_sel_hi:[1,0,1]
	s_waitcnt vmcnt(5)
	v_pk_fma_f32 v[172:173], v[120:121], v[162:163], v[152:153] op_sel_hi:[1,0,1]
	v_pk_fma_f32 v[174:175], v[118:119], v[162:163], v[150:151] op_sel_hi:[1,0,1]
	v_mul_f32_e32 v205, v167, v167
	v_mul_f32_e32 v207, v165, v165
	v_mul_f32_e32 v209, v171, v171
	v_mul_f32_e32 v221, v169, v169
	s_waitcnt vmcnt(4)
	v_pk_fma_f32 v[176:177], v[116:117], v[162:163], v[148:149] op_sel_hi:[1,0,1]
	v_pk_fma_f32 v[162:163], v[114:115], v[162:163], v[146:147] op_sel_hi:[1,0,1]
	v_mul_f32_e32 v222, v175, v175
	v_mul_f32_e32 v224, v173, v173
	v_fmac_f32_e32 v205, v166, v166
	v_fmac_f32_e32 v207, v164, v164
	v_fmac_f32_e32 v209, v170, v170
	v_fmac_f32_e32 v221, v168, v168
	v_mul_f32_e32 v225, v163, v163
	v_mul_f32_e32 v228, v177, v177
	v_fmac_f32_e32 v222, v174, v174
	v_fmac_f32_e32 v224, v172, v172
	v_add_f32_e32 v205, v205, v207
	v_add_f32_e32 v207, v209, v221
	v_fmac_f32_e32 v225, v162, v162
	v_fmac_f32_e32 v228, v176, v176
	v_add_f32_e32 v209, v222, v224
	v_add_f32_e32 v205, v205, v207
	v_add_f32_e32 v221, v225, v228
	v_add_f32_e32 v205, v205, v209
	v_add_f32_e32 v205, v205, v221
	v_mov_b32_e32 v207, v205
	s_nop 1
	v_permlane16_swap_b32_e32 v205, v207
	v_add_f32_e32 v205, v205, v207
	v_mov_b32_e32 v207, v205
	s_nop 1
	v_permlane32_swap_b32_e32 v205, v207
	v_add_f32_e32 v205, v205, v207
	v_fmamk_f32 v205, v205, 0x3c800000, v223
	v_rsq_f32_e32 v222, v205
	v_mul_f32_e32 v221, v218, v199
	v_pk_mul_f32 v[166:167], v[166:167], v[222:223] op_sel_hi:[1,0]
	v_pk_mul_f32 v[164:165], v[164:165], v[222:223] op_sel_hi:[1,0]
	v_pk_mul_f32 v[228:229], v[170:171], v[222:223] op_sel_hi:[1,0]
	v_pk_mul_f32 v[168:169], v[168:169], v[222:223] op_sel_hi:[1,0]
	v_pk_mul_f32 v[230:231], v[174:175], v[222:223] op_sel_hi:[1,0]
	v_pk_mul_f32 v[232:233], v[172:173], v[222:223] op_sel_hi:[1,0]
	v_pk_mul_f32 v[234:235], v[162:163], v[222:223] op_sel_hi:[1,0]
	v_pk_mul_f32 v[236:237], v[176:177], v[222:223] op_sel_hi:[1,0]
	s_waitcnt vmcnt(3)
	v_mov_b64_e32 v[130:131], v[242:243]
	v_mov_b64_e32 v[132:133], v[244:245]
	v_pk_mul_f32 v[172:173], v[132:133], v[164:165]
	v_pk_mul_f32 v[170:171], v[130:131], v[166:167]
	s_waitcnt vmcnt(2)
	v_mov_b64_e32 v[134:135], v[246:247]
	v_mov_b64_e32 v[136:137], v[248:249]
	v_pk_mul_f32 v[176:177], v[136:137], v[168:169]
	v_pk_mul_f32 v[174:175], v[134:135], v[228:229]
	s_waitcnt vmcnt(1)
	v_mov_b64_e32 v[138:139], v[250:251]
	v_mov_b64_e32 v[140:141], v[252:253]
	v_pk_mul_f32 v[164:165], v[140:141], v[232:233]
	v_pk_mul_f32 v[162:163], v[138:139], v[230:231]
	s_waitcnt vmcnt(0)
	v_pk_mul_f32 v[168:169], v[144:145], v[236:237]
	v_pk_mul_f32 v[166:167], v[142:143], v[234:235]
	s_cbranch_vccnz .LBB0_628
	v_ashrrev_i32_e32 v205, 6, v216
	v_cvt_f32_i32_e32 v205, v205
	v_mul_f32_e32 v207, v220, v205
	v_mul_f32_e32 v209, v219, v205
	v_floor_f32_e32 v207, v207
	v_floor_f32_e32 v209, v209
	v_fma_f32 v207, v220, v205, -v207
	v_sin_f32_e32 v228, v207
	v_cos_f32_e32 v230, v207
	v_fma_f32 v207, v219, v205, -v209
	v_sin_f32_e32 v229, v207
	v_cos_f32_e32 v231, v207
	v_mul_f32_e32 v207, v218, v205
	v_floor_f32_e32 v207, v207
	v_pk_mul_f32 v[232:233], v[228:229], v[174:175]
	v_pk_mul_f32 v[174:175], v[230:231], v[174:175]
	v_mul_f32_e32 v222, v197, v205
	v_fma_f32 v207, v218, v205, -v207
	v_floor_f32_e32 v222, v222
	v_pk_fma_f32 v[230:231], v[230:231], v[170:171], v[232:233] neg_lo:[0,0,1] neg_hi:[0,0,1]
	v_pk_fma_f32 v[174:175], v[228:229], v[170:171], v[174:175]
	v_floor_f32_e32 v170, v201
	v_cos_f32_e32 v209, v207
	v_sin_f32_e32 v207, v207
	v_fma_f32 v205, v197, v205, -v222
	v_fma_f32 v171, v220, v199, -v170
	v_sin_f32_e32 v243, v205
	v_cos_f32_e32 v242, v205
	v_sin_f32_e32 v170, v171
	v_cos_f32_e32 v228, v171
	v_floor_f32_e32 v171, v239
	v_fma_f32 v205, v219, v199, -v171
	v_sin_f32_e32 v171, v205
	v_cos_f32_e32 v229, v205
	v_floor_f32_e32 v205, v221
	v_mul_f32_e32 v234, v209, v172
	v_mul_f32_e32 v236, v207, v176
	v_mul_f32_e32 v246, v209, v176
	v_mov_b32_e32 v176, v173
	v_fma_f32 v205, v218, v199, -v205
	v_floor_f32_e32 v209, v240
	v_mul_f32_e32 v244, v207, v172
	v_pk_mul_f32 v[172:173], v[242:243], v[176:177]
	v_cos_f32_e32 v207, v205
	v_sin_f32_e32 v205, v205
	v_fma_f32 v209, v197, v199, -v209
	v_mov_b32_e32 v235, v172
	v_mov_b32_e32 v237, v173
	v_mov_b32_e32 v172, v243
	v_mov_b32_e32 v173, v242
	v_sin_f32_e32 v243, v209
	v_cos_f32_e32 v242, v209
	v_pk_mul_f32 v[172:173], v[172:173], v[176:177]
	v_pk_mul_f32 v[232:233], v[170:171], v[166:167]
	v_mov_b32_e32 v245, v172
	v_mov_b32_e32 v247, v173
	v_pk_add_f32 v[172:173], v[234:235], v[236:237] neg_lo:[0,1] neg_hi:[0,1]
	v_pk_add_f32 v[176:177], v[244:245], v[246:247]
	v_mul_f32_e32 v236, v205, v168
	v_mul_f32_e32 v246, v207, v168
	v_mov_b32_e32 v168, v165
	v_mul_f32_e32 v234, v207, v164
	v_mul_f32_e32 v244, v205, v164
	v_pk_mul_f32 v[164:165], v[242:243], v[168:169]
	v_pk_mul_f32 v[166:167], v[228:229], v[166:167]
	v_mov_b32_e32 v235, v164
	v_mov_b32_e32 v237, v165
	v_mov_b32_e32 v164, v243
	v_mov_b32_e32 v165, v242
	v_pk_mul_f32 v[164:165], v[164:165], v[168:169]
	v_pk_fma_f32 v[228:229], v[228:229], v[162:163], v[232:233] neg_lo:[0,0,1] neg_hi:[0,0,1]
	v_mov_b32_e32 v245, v164
	v_mov_b32_e32 v247, v165
	v_pk_add_f32 v[164:165], v[234:235], v[236:237] neg_lo:[0,1] neg_hi:[0,1]
	v_pk_fma_f32 v[166:167], v[170:171], v[162:163], v[166:167]
	v_pk_add_f32 v[168:169], v[244:245], v[246:247]
	v_mov_b32_e32 v170, v230
	v_mov_b32_e32 v171, v231
	v_mov_b32_e32 v162, v228
	v_mov_b32_e32 v163, v229
